# sample-unit epilogues: row-sum and bf16 residual values prefetched before the partial-sum barrier instead of a load+full wait per unit (KS=2: one load for the four column slots)
# baseline (speedup 1.0000x reference)
.LBB0_397:
	s_ashr_i32 s6, s62, 3
	s_and_b32 s7, s6, 0x3fffff8
	s_and_b32 s66, s62, 7
	s_lshl_b32 s6, s6, 5
	s_or_b32 s7, s7, s66
	s_and_b32 s6, s6, 0xe0
	s_lshl_b32 s66, s7, 6
	v_add_u32_e32 v34, s6, v151
	v_add_u32_e32 v34, 0x2000, v34
	v_or_b32_e32 v38, s66, v152
	v_mul_u32_u24_e32 v39, 0x1080, v34
	v_lshl_add_u32 v38, v38, 1, v39
	global_load_dwordx2 v[36:37], v38, s[14:15]
	v_ashrrev_i32_e32 v35, 31, v34
	v_lshl_add_u64 v[34:35], v[34:35], 3, s[26:27]
	global_load_dwordx2 v[34:35], v[34:35], off
	ds_write_b128 v155, v[30:33]
	ds_write_b128 v155, v[26:29] offset:64
	ds_write_b128 v155, v[14:17] offset:128
	s_nop 2
	ds_write_b128 v155, v[2:5] offset:192
	ds_write_b128 v155, v[6:9] offset:4352
	ds_write_b128 v155, v[10:13] offset:4416
	ds_write_b128 v155, v[22:25] offset:4480
	ds_write_b128 v155, v[18:21] offset:4544
	s_waitcnt lgkmcnt(0)
	s_barrier
	ds_read_b128 v[2:5], v156
	s_ashr_i32 s6, s62, 3
	s_and_b32 s7, s6, 0x3fffff8
	s_and_b32 s66, s62, 7
	s_lshl_b32 s6, s6, 5
	s_waitcnt lgkmcnt(0)
	v_pk_add_f32 v[12:13], v[4:5], 0 op_sel_hi:[1,0]
	v_pk_add_f32 v[14:15], v[2:3], 0 op_sel_hi:[1,0]
	ds_read_b128 v[2:5], v156 offset:8704
	s_or_b32 s7, s7, s66
	s_and_b32 s6, s6, 0xe0
	v_add_u32_e32 v10, s6, v151
	s_lshl_b32 s66, s7, 6
	s_waitcnt lgkmcnt(0)
	v_pk_add_f32 v[12:13], v[12:13], v[4:5]
	v_pk_add_f32 v[14:15], v[14:15], v[2:3]
	ds_read_b128 v[2:5], v156 offset:17408
	v_add_u32_e32 v8, 0x2000, v10
	v_or_b32_e32 v6, s66, v152
	v_ashrrev_i32_e32 v9, 31, v8
	v_ashrrev_i32_e32 v7, 31, v6
	s_waitcnt lgkmcnt(0)
	v_pk_add_f32 v[12:13], v[12:13], v[4:5]
	v_pk_add_f32 v[14:15], v[14:15], v[2:3]
	ds_read_b128 v[2:5], v156 offset:26112
	s_mov_b64 s[6:7], -1
	s_cmp_gt_i32 s84, 1
	s_waitcnt lgkmcnt(0)
	v_pk_add_f32 v[12:13], v[12:13], v[4:5]
	v_pk_add_f32 v[14:15], v[14:15], v[2:3]
	ds_read_b128 v[2:5], v156 offset:34816
	s_waitcnt lgkmcnt(0)
	v_pk_add_f32 v[12:13], v[12:13], v[4:5]
	v_pk_add_f32 v[14:15], v[14:15], v[2:3]
	ds_read_b128 v[2:5], v156 offset:43520
	s_waitcnt lgkmcnt(0)
	v_pk_add_f32 v[12:13], v[12:13], v[4:5]
	v_pk_add_f32 v[14:15], v[14:15], v[2:3]
	ds_read_b128 v[2:5], v156 offset:52224
	s_waitcnt lgkmcnt(0)
	v_pk_add_f32 v[12:13], v[12:13], v[4:5]
	v_pk_add_f32 v[14:15], v[14:15], v[2:3]
	ds_read_b128 v[2:5], v156 offset:60928
	s_waitcnt lgkmcnt(0)
	v_pk_add_f32 v[12:13], v[12:13], v[4:5]
	v_pk_add_f32 v[14:15], v[14:15], v[2:3]
	s_cbranch_scc0 .LBB0_403
	s_waitcnt vmcnt(0)
	v_mov_b32_e32 v2, v34
	v_mov_b32_e32 v3, v35
	v_ffbh_u32_e32 v0, v3
	v_min_u32_e32 v0, 32, v0
	v_lshlrev_b64 v[2:3], v0, v[2:3]
	v_min_u32_e32 v2, 1, v2
	v_or_b32_e32 v2, v3, v2
	v_cvt_f32_u32_e32 v2, v2
	v_sub_u32_e32 v0, 32, v0
	v_ldexp_f32 v0, v2, v0
	v_mul_f32_e32 v0, 0x2f800000, v0
	v_fmamk_f32 v0, v0, 0x3a000000, v171
	v_mul_f32_e32 v2, 0x4f800000, v0
	v_cmp_gt_f32_e32 vcc, s51, v0
	s_nop 1
	v_cndmask_b32_e32 v0, v0, v2, vcc
	v_sqrt_f32_e32 v2, v0
	s_nop 0
	v_add_u32_e32 v3, -1, v2
	v_add_u32_e32 v4, 1, v2
	v_fma_f32 v5, -v3, v2, v0
	v_fma_f32 v11, -v4, v2, v0
	v_cmp_ge_f32_e64 s[6:7], 0, v5
	s_nop 1
	v_cndmask_b32_e64 v2, v2, v3, s[6:7]
	v_cmp_lt_f32_e64 s[6:7], 0, v11
	s_nop 1
	v_cndmask_b32_e64 v2, v2, v4, s[6:7]
	v_mul_f32_e32 v3, 0x37800000, v2
	v_cndmask_b32_e32 v2, v2, v3, vcc
	v_cmp_class_f32_e32 vcc, v0, v172
	s_nop 1
	v_cndmask_b32_e32 v0, v2, v0, vcc
	v_div_scale_f32 v2, s[6:7], v0, v0, 1.0
	v_rcp_f32_e32 v3, v2
	v_div_scale_f32 v4, vcc, 1.0, v0, 1.0
	s_movk_i32 s6, 0x7ff
	v_fma_f32 v5, -v2, v3, 1.0
	v_fmac_f32_e32 v3, v5, v3
	v_mul_f32_e32 v5, v4, v3
	v_fma_f32 v11, -v2, v5, v4
	v_fmac_f32_e32 v5, v11, v3
	v_fma_f32 v2, -v2, v5, v4
	v_div_fmas_f32 v2, v2, v3, v5
	v_cmp_lt_i32_e64 s[6:7], s6, v6
	v_div_fixup_f32 v0, v2, v0, 1.0
	s_and_saveexec_b64 s[70:71], s[6:7]
	s_xor_b64 s[6:7], exec, s[70:71]
	s_cbranch_execz .LBB0_400
	s_cmpk_lt_u32 s66, 0x900
	s_cselect_b64 s[66:67], -1, 0
	s_and_b64 s[66:67], s[66:67], exec
	s_movk_i32 s66, 0xf800
	s_cselect_b32 s66, s66, 0xfffff700
	v_add_u32_e32 v16, s66, v6
	s_mov_b32 s66, 0x24300000
	s_cselect_b32 s66, s66, 0x24800000
	s_mov_b32 s67, 0x4b70000
	s_cselect_b32 s70, s67, 0x4f70000
	s_add_u32 s66, s18, s66
	v_lshl_or_b32 v2, v10, 4, v154
	v_lshlrev_b64 v[18:19], 9, v[8:9]
	s_addc_u32 s67, s19, 0
	v_ashrrev_i32_e32 v17, 31, v16
	v_ashrrev_i32_e32 v3, 31, v2
	v_lshl_add_u64 v[18:19], s[66:67], 0, v[18:19]
	s_add_u32 s66, s16, s70
	v_lshlrev_b64 v[20:21], 10, v[2:3]
	v_lshl_add_u64 v[18:19], v[16:17], 1, v[18:19]
	s_addc_u32 s67, s17, 0
	v_pk_mul_f32 v[4:5], v[12:13], v[0:1] op_sel_hi:[1,0]
	v_pk_mul_f32 v[2:3], v[14:15], v[0:1] op_sel_hi:[1,0]
	s_nop 0
	v_cvt_pk_bf16_f32 v22, v2, v3
	v_cvt_pk_bf16_f32 v23, v4, v5
	global_store_dwordx2 v[18:19], v[22:23], off
	v_lshl_add_u64 v[18:19], s[66:67], 0, v[20:21]
	v_lshl_add_u64 v[16:17], v[16:17], 2, v[18:19]
	global_store_dwordx4 v[16:17], v[2:5], off

.LBB0_403:
	s_andn2_b64 vcc, exec, s[6:7]
	s_cbranch_vccnz .LBB0_385
	s_cmp_eq_u32 s84, 1
	s_mov_b64 s[6:7], -1
	s_cbranch_scc1 .LBB0_412
	v_mov_b64_e32 v[2:3], s[14:15]
	v_mad_i64_i32 v[2:3], s[6:7], v8, s33, v[2:3]
	v_lshl_add_u64 v[16:17], v[6:7], 1, v[2:3]
	s_andn2_b64 vcc, exec, s[38:39]
	s_mov_b64 s[6:7], -1
	s_cbranch_vccnz .LBB0_407
	s_mov_b64 s[6:7], 0
	s_waitcnt vmcnt(0)
	v_mov_b32_e32 v4, v36
	v_mov_b32_e32 v5, v37
	v_lshlrev_b32_e32 v2, 16, v4
	v_and_b32_e32 v3, 0xffff0000, v4
	v_lshlrev_b32_e32 v4, 16, v5
	v_and_b32_e32 v5, 0xffff0000, v5

.LBB0_431:
	s_mov_b32 s62, 0
	s_mov_b32 s66, s2
	s_ashr_i32 s4, s2, 3
	s_lshl_b32 s4, s4, 5
	s_and_b32 s4, s4, 0xe0
	v_add_u32_e32 v34, s4, v163
	v_add_u32_e32 v34, 0x2000, v34
	v_ashrrev_i32_e32 v35, 31, v34
	v_lshl_add_u64 v[34:35], v[34:35], 3, s[26:27]
	global_load_dwordx2 v[34:35], v[34:35], off
	ds_write_b128 v168, v[30:33]
	ds_write_b128 v168, v[26:29] offset:64
	ds_write_b128 v168, v[14:17] offset:128
	s_nop 1
	ds_write_b128 v168, v[2:5] offset:192
	ds_write_b128 v168, v[6:9] offset:4352
	ds_write_b128 v168, v[10:13] offset:4416
	ds_write_b128 v168, v[22:25] offset:4480
	ds_write_b128 v168, v[18:21] offset:4544
	s_waitcnt lgkmcnt(0)
	s_barrier
	s_branch .LBB0_434

.LBB0_450:
	s_and_b64 vcc, exec, s[4:5]
	s_cbranch_vccz .LBB0_432
	s_waitcnt lgkmcnt(0)
	s_cmp_lg_u32 s62, 0
	s_cbranch_scc1 .Lsg2_nw
	s_waitcnt vmcnt(0)
.Lsg2_nw:
	v_mov_b32_e32 v2, v34
	v_mov_b32_e32 v3, v35
	v_ffbh_u32_e32 v0, v3
	v_min_u32_e32 v0, 32, v0
	v_lshlrev_b64 v[2:3], v0, v[2:3]
	v_min_u32_e32 v2, 1, v2
	v_or_b32_e32 v2, v3, v2
	v_cvt_f32_u32_e32 v2, v2
	v_sub_u32_e32 v0, 32, v0
	v_ldexp_f32 v0, v2, v0
	v_mul_f32_e32 v0, 0x2f800000, v0
	v_fmamk_f32 v0, v0, 0x3a000000, v171
	v_cmp_gt_f32_e32 vcc, s51, v0
	v_mul_f32_e32 v2, 0x4f800000, v0
	s_nop 0
	v_cndmask_b32_e32 v0, v0, v2, vcc
	v_sqrt_f32_e32 v2, v0
	s_nop 0
	v_add_u32_e32 v3, -1, v2
	v_fma_f32 v4, -v3, v2, v0
	v_cmp_ge_f32_e64 s[4:5], 0, v4
	v_add_u32_e32 v4, 1, v2
	s_nop 0
	v_cndmask_b32_e64 v3, v2, v3, s[4:5]
	v_fma_f32 v2, -v4, v2, v0
	v_cmp_lt_f32_e64 s[4:5], 0, v2
	s_nop 1
	v_cndmask_b32_e64 v2, v3, v4, s[4:5]
	v_mul_f32_e32 v3, 0x37800000, v2
	v_cndmask_b32_e32 v2, v2, v3, vcc
	v_cmp_class_f32_e32 vcc, v0, v172
	s_nop 1
	v_cndmask_b32_e32 v0, v2, v0, vcc
	v_div_scale_f32 v2, s[4:5], v0, v0, 1.0
	v_rcp_f32_e32 v3, v2
	s_movk_i32 s4, 0x4080
	v_fma_f32 v4, -v2, v3, 1.0
	v_fmac_f32_e32 v3, v4, v3
	v_div_scale_f32 v4, vcc, 1.0, v0, 1.0
	v_mul_f32_e32 v5, v4, v3
	v_fma_f32 v9, -v2, v5, v4
	v_fmac_f32_e32 v5, v9, v3
	v_fma_f32 v2, -v2, v5, v4
	v_div_fmas_f32 v2, v2, v3, v5
	v_div_fixup_f32 v0, v2, v0, 1.0
	v_pk_mul_f32 v[2:3], v[10:11], v[0:1] op_sel_hi:[1,0]
	v_pk_mul_f32 v[4:5], v[12:13], v[0:1] op_sel_hi:[1,0]
	v_max_f32_e32 v2, 0, v2
	v_max_f32_e32 v0, 0, v4
	v_max_f32_e32 v4, 0, v5
	v_mul_f32_e32 v5, v2, v2
	v_max_f32_e32 v2, 0, v3
	v_mul_f32_e32 v4, v4, v4
	v_mul_f32_e32 v3, v2, v2
	v_mul_f32_e32 v0, v0, v0
	v_cvt_pk_bf16_f32 v2, v0, v4
	v_cvt_pk_bf16_f32 v3, v5, v3
	v_mov_b64_e32 v[4:5], s[44:45]
	v_mad_i64_i32 v[4:5], s[4:5], v8, s4, v[4:5]
	v_lshl_add_u64 v[4:5], v[6:7], 1, v[4:5]
	global_store_dwordx2 v[4:5], v[2:3], off
	s_branch .LBB0_432
